# stagger GEMM tile boundaries inside each XCD (per-pm start delay) in swiglu phases so store bursts do not collide
# speedup vs baseline: 1.0050x; 1.0050x over previous
; #define PG8_STAGE(bufoff, gbase, voff) do { _Pragma("unroll") for (int _i = 0; _i < 2; ++_i) \
;         __builtin_amdgcn_global_load_lds((const unsigned*)((const char*)(gbase) + (voff)[_i]), (PG8_LAS unsigned*)(lds + (bufoff) + ldsw + _i * 8192), 16, 0, 0); } while (0)
; #define PG8_WAIT_V(n) asm volatile("s_waitcnt vmcnt(" #n ")" ::: "memory")
; #define PG8_BAR __builtin_amdgcn_s_barrier()
; template <class Epi, class Sched>
; __device__ __forceinline__ void gemm_phase(PG8_LAS unsigned char* lds, const Gemm g, const Sched& S, const Epi& E) {
;     ...
;     for (int i = 0; i < 2; ++i) { int R, C; stage_rc(tid * 16 + i * 8192, R, C); const int Rb = Epi::PERM ? ((R & ~31) + perm32(R & 31)) : R;
;         voffA[i] = (unsigned)(R * g.lda + C) * 2u; voffB[i] = (unsigned)(Rb * K + C) * 2u; }
;     const size_t kstep = (size_t)(BK * 2);
;     const size_t hstepA = (size_t)HALF * g.lda * 2, hstepB = (size_t)HALF * K * 2;
;     const size_t tstepA = 2 * hstepA, tstepB = 2 * hstepB;
;     const unsigned ldsw = (unsigned)wid * 1024u;
;     const int aoff = lds_byte(wr * 64 + fr, fq * 8), boff = lds_byte(wc * 32 + fr, fq * 8);
;     ...
;     Unit cur, nxt; int ui = 0;
;     if (!S.next(0, cur)) return;
;     f32x4 acc[2][2][4][2];
; #pragma unroll
;     for (int a = 0; a < 2; ++a)
; #pragma unroll
;         for (int b = 0; b < 2; ++b)
; #pragma unroll
;             for (int m = 0; m < 4; ++m)
; #pragma unroll
;                 for (int n = 0; n < 2; ++n) acc[a][b][m][n] = (f32x4){0.f, 0.f, 0.f, 0.f};
;     bf16x8 At[4][2], B0[2][2], B1[2][2];
;     const char* cA = (const char*)g.A + (size_t)cur.pm * tstepA + (g.agroup ? (size_t)(cur.pn / g.agroup) * K * 2 : (size_t)0); const char* cB = (const char*)g.Bt + (size_t)cur.pn * tstepB;
;     S.a_ready(cur);
;     PG8_STAGE(PG8_SB(0, 0), cB, voffB); PG8_STAGE(PG8_SA(0, 0), cA, voffA); PG8_STAGE(PG8_SB(0, 1), cB + hstepB, voffB); PG8_STAGE(PG8_SA(0, 1), cA + hstepA, voffA);
;     if (wr == 1) PG8_BAR;
;     PG8_WAIT_V(4); PG8_BAR;
;     PG8_STAGE(PG8_SB(1, 0), cB + kstep, voffB); PG8_STAGE(PG8_SA(1, 0), cA + kstep, voffA); PG8_STAGE(PG8_SB(1, 1), cB + hstepB + kstep, voffB);
; __global__ void __launch_bounds__(NTHR) fwd_kernel(Args a_k) {
;     ...
;     if (PHEN(5) && IN(5)) for (int rep_ = 0; rep_ < NREP(5); ++rep_) { if (rep_) xcd_barrier(xbar); LDA_ EpiSwiglu e{R, DFF}; GEMM(EpiSwiglu, e, XN, ws + WS_WGU, T_, 2 * DFF, D_, D_, 0); } SEAM(5);
.LBB0_474:
	s_cmp_lt_i32 s62, 6
	s_cselect_b64 s[6:7], -1, 0
	s_and_b64 s[8:9], s[6:7], s[8:9]
	s_andn2_b64 vcc, exec, s[8:9]
	s_cbranch_vccnz .LBB0_487
	s_lshr_b32 s98, s2, 3
	s_and_b32 s98, s98, 3
	s_mul_i32 s98, s98, 10
	s_cmp_eq_u32 s98, 0
	s_cbranch_scc1 .Lstg5_done
.Lstg5_loop:
	s_sleep 8
	s_sub_u32 s98, s98, 1
	s_cmp_lg_u32 s98, 0
	s_cbranch_scc1 .Lstg5_loop
.Lstg5_done:
	s_cmpk_gt_i32 s2, 0xaff
	v_mov_b32_e32 v2, v1
	s_mov_b64 s[6:7], s[0:1]
	v_readfirstlane_b32 s3, v1
	s_cbranch_scc1 .LBB0_487
	v_lshrrev_b32_e32 v4, 1, v1
	v_and_b32_e32 v13, 24, v4
	v_lshrrev_b32_e32 v4, 5, v1
	v_and_b32_e32 v4, 4, v4
	v_bfe_u32 v5, v1, 2, 2
	v_lshlrev_b32_e32 v2, 4, v1
	v_and_b32_e32 v3, 32, v1
	v_bfe_u32 v12, v1, 2, 4
	v_or3_b32 v4, v4, v5, v13
	v_lshrrev_b32_e32 v5, 3, v1
	s_movk_i32 s10, 0x70
	v_bitop3_b32 v10, v2, v3, 48 bitop3:0x6c
	v_and_b32_e32 v11, 64, v1
	v_and_or_b32 v6, v5, s10, v12
	s_movk_i32 s10, 0x60
	v_add_u32_e32 v14, 0x2000, v2
	v_or_b32_e32 v3, v10, v11
	v_and_or_b32 v5, v5, s10, v4
	v_lshrrev_b32_e32 v2, 7, v14
	s_movk_i32 s10, 0xf0
	v_lshl_or_b32 v132, v5, 12, v3
	v_and_or_b32 v5, v2, s10, v12
	s_load_dwordx2 s[10:11], s[6:7], 0xc8
	s_movk_i32 s6, 0xe0
	v_and_or_b32 v2, v2, s6, v4
	s_movk_i32 s38, 0x161
	v_lshl_or_b32 v136, v2, 12, v3
	s_waitcnt lgkmcnt(0)
	s_add_u32 s30, s10, 0x10dcc000
	s_addc_u32 s31, s11, 0
	s_add_u32 s34, s10, 0x650c000
	s_addc_u32 s35, s11, 0
	s_ashr_i32 s37, s2, 31
	s_lshr_b32 s6, s37, 29
	s_add_i32 s6, s2, s6
	s_lshr_b32 s12, s3, 6
	s_ashr_i32 s13, s6, 3
	s_and_b32 s6, s6, -8
	s_lshr_b32 s7, s3, 8
	s_lshl_b32 s36, s12, 10
	s_sub_i32 s6, s2, s6
	s_cmp_lt_i32 s6, 0
	s_cselect_b32 s14, s38, 0x160
	s_mul_i32 s6, s6, s14
	s_add_i32 s6, s6, s13
	s_mul_hi_i32 s13, s6, 0x2e8ba2e9
	s_lshr_b32 s14, s13, 31
	s_ashr_i32 s13, s13, 5
	s_add_i32 s13, s13, s14
	s_lshl_b32 s14, s13, 2
	s_mulk_i32 s13, 0xb0
	s_sub_i32 s13, s6, s13
	s_sext_i32_i16 s6, s13
	s_bfe_u32 s6, s6, 0x2001d
	s_add_i32 s15, s13, s6
	s_sext_i32_i16 s6, s15
	s_and_b32 s15, s15, 0xfffc
	s_sub_i32 s13, s13, s15
	s_sext_i32_i16 s13, s13
	s_lshr_b32 s6, s6, 2
	s_add_i32 s22, s14, s13
	s_ashr_i32 s23, s22, 31
	s_bfe_i64 s[16:17], s[6:7], 0x100000
	s_lshl_b64 s[14:15], s[22:23], 20
	s_lshl_b64 s[16:17], s[16:17], 20
	s_add_u32 s26, s34, s16
	s_addc_u32 s27, s35, s17
	s_add_i32 s23, s36, 0
	s_add_i32 m0, s23, 0x10000
	v_lshl_or_b32 v130, v6, 12, v3
	global_load_lds_dwordx4 v132, s[26:27]
	s_add_i32 m0, s23, 0x12000
	s_add_u32 s24, s30, s14
	global_load_lds_dwordx4 v136, s[26:27]
	s_addc_u32 s25, s31, s15
	s_mov_b32 m0, s23
	s_add_i32 s39, s23, 0x2000
	v_lshl_or_b32 v134, v5, 12, v3
	global_load_lds_dwordx4 v130, s[24:25]
	s_mov_b32 m0, s39
	s_add_u32 s14, s26, 0x80000
	global_load_lds_dwordx4 v134, s[24:25]
	s_addc_u32 s15, s27, 0
	s_add_i32 m0, s23, 0x14000
	v_mov_b32_e32 v133, 0
	global_load_lds_dwordx4 v132, s[14:15]
	s_add_i32 m0, s23, 0x16000
	v_mov_b32_e32 v137, v133
	global_load_lds_dwordx4 v136, s[14:15]
	s_add_u32 s14, s24, 0x80000
	s_addc_u32 s15, s25, 0
	s_add_i32 s40, s23, 0x4000
	s_mov_b32 m0, s40
	s_add_i32 s41, s23, 0x6000
	global_load_lds_dwordx4 v130, s[14:15]
	s_mov_b32 m0, s41
	v_mov_b32_e32 v131, v133
	global_load_lds_dwordx4 v134, s[14:15]
	v_mov_b32_e32 v135, v133
	s_mov_b32 s42, 0
	v_lshl_add_u64 v[8:9], s[26:27], 0, v[132:133]
	v_lshl_add_u64 v[6:7], s[26:27], 0, v[136:137]
	v_lshl_add_u64 v[4:5], s[24:25], 0, v[130:131]
	s_cmp_lg_u32 s7, 1
	v_lshl_add_u64 v[2:3], s[24:25], 0, v[134:135]
	s_cbranch_scc1 .LBB0_478
	s_barrier

; #define SEAM(k) do { if (IN(k) && IN((k) + 1)) xcd_barrier(xbar); } while (0)
; #define GEMM(EpiT, epi, Aptr, Bptr, M_, N_, K_, lda_, agr_) do { pg8::Gemm g_{(const bf16_t*)(Aptr), (const bf16_t*)(Bptr), (M_), (N_), (K_), (lda_), (agr_)}; pg8::StaticOrder S_; S_.init((M_), (N_), G, bx); \
;         pg8::gemm_phase<EpiT, pg8::StaticOrder>(ldsl, g_, S_, epi); } while (0)
; __global__ void __launch_bounds__(NTHR) fwd_kernel(Args a_k) {
;     ...
;     if (PHEN(16) && IN(16)) for (int rep_ = 0; rep_ < NREP(16); ++rep_) { if (rep_) xcd_barrier(xbar); LDA_ EpiSwiglu e{R, DFF}; GEMM(EpiSwiglu, e, XN, ws + WS_WGU + (size_t)2 * DFF * D_ * 2, T_, 2 * DFF, D_, D_, 0); } SEAM(16);
.LBB0_1171:
	s_cmp_lt_i32 s62, 17
	s_cselect_b64 s[6:7], -1, 0
	s_and_b64 s[8:9], s[6:7], s[8:9]
	s_andn2_b64 vcc, exec, s[8:9]
	s_cbranch_vccnz .LBB0_1184
	s_lshr_b32 s98, s2, 3
	s_and_b32 s98, s98, 3
	s_mul_i32 s98, s98, 10
	s_cmp_eq_u32 s98, 0
	s_cbranch_scc1 .Lstg16_done

; #define PG8_STAGE(bufoff, gbase, voff) do { _Pragma("unroll") for (int _i = 0; _i < 2; ++_i) \
;         __builtin_amdgcn_global_load_lds((const unsigned*)((const char*)(gbase) + (voff)[_i]), (PG8_LAS unsigned*)(lds + (bufoff) + ldsw + _i * 8192), 16, 0, 0); } while (0)
; #define PG8_WAIT_V(n) asm volatile("s_waitcnt vmcnt(" #n ")" ::: "memory")
; template <class Epi, class Sched>
; __device__ __forceinline__ void gemm_phase(PG8_LAS unsigned char* lds, const Gemm g, const Sched& S, const Epi& E) {
;     ...
;     for (int i = 0; i < 2; ++i) { int R, C; stage_rc(tid * 16 + i * 8192, R, C); const int Rb = Epi::PERM ? ((R & ~31) + perm32(R & 31)) : R;
;         voffA[i] = (unsigned)(R * g.lda + C) * 2u; voffB[i] = (unsigned)(Rb * K + C) * 2u; }
;     const size_t kstep = (size_t)(BK * 2);
;     const size_t hstepA = (size_t)HALF * g.lda * 2, hstepB = (size_t)HALF * K * 2;
;     const size_t tstepA = 2 * hstepA, tstepB = 2 * hstepB;
;     const unsigned ldsw = (unsigned)wid * 1024u;
;     const int aoff = lds_byte(wr * 64 + fr, fq * 8), boff = lds_byte(wc * 32 + fr, fq * 8);
;     ...
;     Unit cur, nxt; int ui = 0;
;     if (!S.next(0, cur)) return;
;     f32x4 acc[2][2][4][2];
; #pragma unroll
;     for (int a = 0; a < 2; ++a)
; #pragma unroll
;         for (int b = 0; b < 2; ++b)
; #pragma unroll
;             for (int m = 0; m < 4; ++m)
; #pragma unroll
;                 for (int n = 0; n < 2; ++n) acc[a][b][m][n] = (f32x4){0.f, 0.f, 0.f, 0.f};
;     bf16x8 At[4][2], B0[2][2], B1[2][2];
;     const char* cA = (const char*)g.A + (size_t)cur.pm * tstepA + (g.agroup ? (size_t)(cur.pn / g.agroup) * K * 2 : (size_t)0); const char* cB = (const char*)g.Bt + (size_t)cur.pn * tstepB;
;     S.a_ready(cur);
;     PG8_STAGE(PG8_SB(0, 0), cB, voffB); PG8_STAGE(PG8_SA(0, 0), cA, voffA); PG8_STAGE(PG8_SB(0, 1), cB + hstepB, voffB); PG8_STAGE(PG8_SA(0, 1), cA + hstepA, voffA);
;     if (wr == 1) PG8_BAR;
;     PG8_WAIT_V(4); PG8_BAR;
;     PG8_STAGE(PG8_SB(1, 0), cB + kstep, voffB); PG8_STAGE(PG8_SA(1, 0), cA + kstep, voffA); PG8_STAGE(PG8_SB(1, 1), cB + hstepB + kstep, voffB);
; __global__ void __launch_bounds__(NTHR) fwd_kernel(Args a_k) {
;     ...
;     if (PHEN(16) && IN(16)) for (int rep_ = 0; rep_ < NREP(16); ++rep_) { if (rep_) xcd_barrier(xbar); LDA_ EpiSwiglu e{R, DFF}; GEMM(EpiSwiglu, e, XN, ws + WS_WGU + (size_t)2 * DFF * D_ * 2, T_, 2 * DFF, D_, D_, 0); } SEAM(16);
.Lstg16_done:
	s_cmpk_gt_i32 s2, 0xaff
	v_mov_b32_e32 v2, v1
	s_mov_b64 s[6:7], s[0:1]
	v_readfirstlane_b32 s3, v1
	s_cbranch_scc1 .LBB0_1184
	v_lshrrev_b32_e32 v4, 1, v1
	v_and_b32_e32 v13, 24, v4
	v_lshrrev_b32_e32 v4, 5, v1
	v_and_b32_e32 v4, 4, v4
	v_bfe_u32 v5, v1, 2, 2
	v_lshlrev_b32_e32 v2, 4, v1
	v_and_b32_e32 v3, 32, v1
	v_bfe_u32 v12, v1, 2, 4
	v_or3_b32 v4, v4, v5, v13
	v_lshrrev_b32_e32 v5, 3, v1
	s_movk_i32 s10, 0x70
	v_bitop3_b32 v10, v2, v3, 48 bitop3:0x6c
	v_and_b32_e32 v11, 64, v1
	v_and_or_b32 v6, v5, s10, v12
	s_movk_i32 s10, 0x60
	v_add_u32_e32 v14, 0x2000, v2
	v_or_b32_e32 v3, v10, v11
	v_and_or_b32 v5, v5, s10, v4
	v_lshrrev_b32_e32 v2, 7, v14
	s_movk_i32 s10, 0xf0
	s_waitcnt vmcnt(0)
	v_lshl_or_b32 v132, v5, 12, v3
	v_and_or_b32 v5, v2, s10, v12
	s_load_dwordx2 s[10:11], s[6:7], 0xc8
	s_movk_i32 s6, 0xe0
	v_and_or_b32 v2, v2, s6, v4
	s_movk_i32 s38, 0x161
	v_lshl_or_b32 v136, v2, 12, v3
	s_waitcnt lgkmcnt(0)
	s_add_u32 s30, s10, 0x10dcc000
	s_addc_u32 s31, s11, 0
	s_add_u32 s34, s10, 0x910c000
	s_addc_u32 s35, s11, 0
	s_ashr_i32 s37, s2, 31
	s_lshr_b32 s6, s37, 29
	s_add_i32 s6, s2, s6
	s_lshr_b32 s12, s3, 6
	s_ashr_i32 s13, s6, 3
	s_and_b32 s6, s6, -8
	s_lshr_b32 s7, s3, 8
	s_lshl_b32 s36, s12, 10
	s_sub_i32 s6, s2, s6
	s_cmp_lt_i32 s6, 0
	s_cselect_b32 s14, s38, 0x160
	s_mul_i32 s6, s6, s14
	s_add_i32 s6, s6, s13
	s_mul_hi_i32 s13, s6, 0x2e8ba2e9
	s_lshr_b32 s14, s13, 31
	s_ashr_i32 s13, s13, 5
	s_add_i32 s13, s13, s14
	s_lshl_b32 s14, s13, 2
	s_mulk_i32 s13, 0xb0
	s_sub_i32 s13, s6, s13
	s_sext_i32_i16 s6, s13
	s_bfe_u32 s6, s6, 0x2001d
	s_add_i32 s15, s13, s6
	s_sext_i32_i16 s6, s15
	s_and_b32 s15, s15, 0xfffc
	s_sub_i32 s13, s13, s15
	s_sext_i32_i16 s13, s13
	s_lshr_b32 s6, s6, 2
	s_add_i32 s22, s14, s13
	s_ashr_i32 s23, s22, 31
	s_bfe_i64 s[16:17], s[6:7], 0x100000
	s_lshl_b64 s[14:15], s[22:23], 20
	s_lshl_b64 s[16:17], s[16:17], 20
	s_add_u32 s26, s34, s16
	s_addc_u32 s27, s35, s17
	s_add_i32 s23, s36, 0
	s_add_i32 m0, s23, 0x10000
	v_lshl_or_b32 v130, v6, 12, v3
	global_load_lds_dwordx4 v132, s[26:27]
	s_add_i32 m0, s23, 0x12000
	s_add_u32 s24, s30, s14
	global_load_lds_dwordx4 v136, s[26:27]
	s_addc_u32 s25, s31, s15
	s_mov_b32 m0, s23
	s_add_i32 s39, s23, 0x2000
	v_lshl_or_b32 v134, v5, 12, v3
	global_load_lds_dwordx4 v130, s[24:25]
	s_mov_b32 m0, s39
	s_add_u32 s14, s26, 0x80000
	global_load_lds_dwordx4 v134, s[24:25]
	s_addc_u32 s15, s27, 0
	s_add_i32 m0, s23, 0x14000
	v_mov_b32_e32 v133, 0
	global_load_lds_dwordx4 v132, s[14:15]
	s_add_i32 m0, s23, 0x16000
	v_mov_b32_e32 v137, v133
	global_load_lds_dwordx4 v136, s[14:15]
	s_add_u32 s14, s24, 0x80000
	s_addc_u32 s15, s25, 0
	s_add_i32 s40, s23, 0x4000
	s_mov_b32 m0, s40
	s_add_i32 s41, s23, 0x6000
	global_load_lds_dwordx4 v130, s[14:15]
	s_mov_b32 m0, s41
	v_mov_b32_e32 v131, v133
	global_load_lds_dwordx4 v134, s[14:15]
	v_mov_b32_e32 v135, v133
	s_mov_b32 s42, 0
	v_lshl_add_u64 v[8:9], s[26:27], 0, v[132:133]
	v_lshl_add_u64 v[6:7], s[26:27], 0, v[136:137]
	v_lshl_add_u64 v[4:5], s[24:25], 0, v[130:131]
	s_cmp_lg_u32 s7, 1
	v_lshl_add_u64 v[2:3], s[24:25], 0, v[134:135]
	s_cbranch_scc1 .LBB0_1175
	s_barrier
